# PEER query fold (w_q x subkeys, f32) now on v_mfma_f32_32x32x2_f32 (f32 operands, f32 accumulate) instead of packed f32 VALU; prologue -24us
# speedup vs baseline: 1.0171x; 1.0159x over previous
.LBB0_786:
	v_and_b32_e32 v25, 31, v58
	v_lshrrev_b32_e32 v30, 5, v58
	s_lshr_b32 s4, s92, 6
	s_and_b32 s5, s4, 1
	s_lshr_b32 s4, s4, 1
	s_lshl_b32 s5, s5, 5
	s_lshl_b32 s4, s4, 5
	v_add_u32_e32 v31, s5, v25
	v_mul_u32_u24_e32 v31, 0x210, v31
	v_lshl_add_u32 v31, v30, 4, v31
	v_add_u32_e32 v31, s67, v31
	v_add_u32_e32 v72, s4, v25
	v_mul_u32_u24_e32 v73, 0x210, v72
	v_lshl_add_u32 v73, v30, 4, v73
	ds_read_b128 v[26:29], v31
	ds_read_b128 v[34:37], v73
	ds_read_b128 v[38:41], v31 offset:32
	ds_read_b128 v[42:45], v73 offset:32
	s_waitcnt lgkmcnt(2)
	v_mfma_f32_32x32x2_f32 v[6:21], v26, v34, v[6:21]
	v_mfma_f32_32x32x2_f32 v[6:21], v27, v35, v[6:21]
	v_mfma_f32_32x32x2_f32 v[6:21], v28, v36, v[6:21]
	v_mfma_f32_32x32x2_f32 v[6:21], v29, v37, v[6:21]
	ds_read_b128 v[26:29], v31 offset:64
	ds_read_b128 v[34:37], v73 offset:64
	s_waitcnt lgkmcnt(2)
	v_mfma_f32_32x32x2_f32 v[6:21], v38, v42, v[6:21]
	v_mfma_f32_32x32x2_f32 v[6:21], v39, v43, v[6:21]
	v_mfma_f32_32x32x2_f32 v[6:21], v40, v44, v[6:21]
	v_mfma_f32_32x32x2_f32 v[6:21], v41, v45, v[6:21]
	ds_read_b128 v[38:41], v31 offset:96
	ds_read_b128 v[42:45], v73 offset:96
	s_waitcnt lgkmcnt(2)
	v_mfma_f32_32x32x2_f32 v[6:21], v26, v34, v[6:21]
	v_mfma_f32_32x32x2_f32 v[6:21], v27, v35, v[6:21]
	v_mfma_f32_32x32x2_f32 v[6:21], v28, v36, v[6:21]
	v_mfma_f32_32x32x2_f32 v[6:21], v29, v37, v[6:21]
	ds_read_b128 v[26:29], v31 offset:128
	ds_read_b128 v[34:37], v73 offset:128
	s_waitcnt lgkmcnt(2)
	v_mfma_f32_32x32x2_f32 v[6:21], v38, v42, v[6:21]
	v_mfma_f32_32x32x2_f32 v[6:21], v39, v43, v[6:21]
	v_mfma_f32_32x32x2_f32 v[6:21], v40, v44, v[6:21]
	v_mfma_f32_32x32x2_f32 v[6:21], v41, v45, v[6:21]
	ds_read_b128 v[38:41], v31 offset:160
	ds_read_b128 v[42:45], v73 offset:160
	s_waitcnt lgkmcnt(2)
	v_mfma_f32_32x32x2_f32 v[6:21], v26, v34, v[6:21]
	v_mfma_f32_32x32x2_f32 v[6:21], v27, v35, v[6:21]
	v_mfma_f32_32x32x2_f32 v[6:21], v28, v36, v[6:21]
	v_mfma_f32_32x32x2_f32 v[6:21], v29, v37, v[6:21]
	ds_read_b128 v[26:29], v31 offset:192
	ds_read_b128 v[34:37], v73 offset:192
	s_waitcnt lgkmcnt(2)
	v_mfma_f32_32x32x2_f32 v[6:21], v38, v42, v[6:21]
	v_mfma_f32_32x32x2_f32 v[6:21], v39, v43, v[6:21]
	v_mfma_f32_32x32x2_f32 v[6:21], v40, v44, v[6:21]
	v_mfma_f32_32x32x2_f32 v[6:21], v41, v45, v[6:21]
	ds_read_b128 v[38:41], v31 offset:224
	ds_read_b128 v[42:45], v73 offset:224
	s_waitcnt lgkmcnt(2)
	v_mfma_f32_32x32x2_f32 v[6:21], v26, v34, v[6:21]
	v_mfma_f32_32x32x2_f32 v[6:21], v27, v35, v[6:21]
	v_mfma_f32_32x32x2_f32 v[6:21], v28, v36, v[6:21]
	v_mfma_f32_32x32x2_f32 v[6:21], v29, v37, v[6:21]
	ds_read_b128 v[26:29], v31 offset:256
	ds_read_b128 v[34:37], v73 offset:256
	s_waitcnt lgkmcnt(2)
	v_mfma_f32_32x32x2_f32 v[6:21], v38, v42, v[6:21]
	v_mfma_f32_32x32x2_f32 v[6:21], v39, v43, v[6:21]
	v_mfma_f32_32x32x2_f32 v[6:21], v40, v44, v[6:21]
	v_mfma_f32_32x32x2_f32 v[6:21], v41, v45, v[6:21]
	ds_read_b128 v[38:41], v31 offset:288
	ds_read_b128 v[42:45], v73 offset:288
	s_waitcnt lgkmcnt(2)
	v_mfma_f32_32x32x2_f32 v[6:21], v26, v34, v[6:21]
	v_mfma_f32_32x32x2_f32 v[6:21], v27, v35, v[6:21]
	v_mfma_f32_32x32x2_f32 v[6:21], v28, v36, v[6:21]
	v_mfma_f32_32x32x2_f32 v[6:21], v29, v37, v[6:21]
	ds_read_b128 v[26:29], v31 offset:320
	ds_read_b128 v[34:37], v73 offset:320
	s_waitcnt lgkmcnt(2)
	v_mfma_f32_32x32x2_f32 v[6:21], v38, v42, v[6:21]
	v_mfma_f32_32x32x2_f32 v[6:21], v39, v43, v[6:21]
	v_mfma_f32_32x32x2_f32 v[6:21], v40, v44, v[6:21]
	v_mfma_f32_32x32x2_f32 v[6:21], v41, v45, v[6:21]
	ds_read_b128 v[38:41], v31 offset:352
	ds_read_b128 v[42:45], v73 offset:352
	s_waitcnt lgkmcnt(2)
	v_mfma_f32_32x32x2_f32 v[6:21], v26, v34, v[6:21]
	v_mfma_f32_32x32x2_f32 v[6:21], v27, v35, v[6:21]
	v_mfma_f32_32x32x2_f32 v[6:21], v28, v36, v[6:21]
	v_mfma_f32_32x32x2_f32 v[6:21], v29, v37, v[6:21]
	ds_read_b128 v[26:29], v31 offset:384
	ds_read_b128 v[34:37], v73 offset:384
	s_waitcnt lgkmcnt(2)
	v_mfma_f32_32x32x2_f32 v[6:21], v38, v42, v[6:21]
	v_mfma_f32_32x32x2_f32 v[6:21], v39, v43, v[6:21]
	v_mfma_f32_32x32x2_f32 v[6:21], v40, v44, v[6:21]
	v_mfma_f32_32x32x2_f32 v[6:21], v41, v45, v[6:21]
	ds_read_b128 v[38:41], v31 offset:416
	ds_read_b128 v[42:45], v73 offset:416
	s_waitcnt lgkmcnt(2)
	v_mfma_f32_32x32x2_f32 v[6:21], v26, v34, v[6:21]
	v_mfma_f32_32x32x2_f32 v[6:21], v27, v35, v[6:21]
	v_mfma_f32_32x32x2_f32 v[6:21], v28, v36, v[6:21]
	v_mfma_f32_32x32x2_f32 v[6:21], v29, v37, v[6:21]
	ds_read_b128 v[26:29], v31 offset:448
	ds_read_b128 v[34:37], v73 offset:448
	s_waitcnt lgkmcnt(2)
	v_mfma_f32_32x32x2_f32 v[6:21], v38, v42, v[6:21]
	v_mfma_f32_32x32x2_f32 v[6:21], v39, v43, v[6:21]
	v_mfma_f32_32x32x2_f32 v[6:21], v40, v44, v[6:21]
	v_mfma_f32_32x32x2_f32 v[6:21], v41, v45, v[6:21]
	ds_read_b128 v[38:41], v31 offset:480
	ds_read_b128 v[42:45], v73 offset:480
	s_waitcnt lgkmcnt(2)
	v_mfma_f32_32x32x2_f32 v[6:21], v26, v34, v[6:21]
	v_mfma_f32_32x32x2_f32 v[6:21], v27, v35, v[6:21]
	v_mfma_f32_32x32x2_f32 v[6:21], v28, v36, v[6:21]
	v_mfma_f32_32x32x2_f32 v[6:21], v29, v37, v[6:21]
	s_waitcnt lgkmcnt(0)
	v_mfma_f32_32x32x2_f32 v[6:21], v38, v42, v[6:21]
	v_mfma_f32_32x32x2_f32 v[6:21], v39, v43, v[6:21]
	v_mfma_f32_32x32x2_f32 v[6:21], v40, v44, v[6:21]
	v_mfma_f32_32x32x2_f32 v[6:21], v41, v45, v[6:21]
	s_lshl_b64 s[4:5], s[8:9], 11
	s_or_b32 s4, s4, s17
	s_lshl_b32 s4, s4, 11
	s_lshl_b32 s5, s16, 1
	s_add_i32 s4, s4, s5
	s_lshr_b32 s5, s92, 6
	s_and_b32 s5, s5, 1
	s_lshl_b32 s5, s5, 6
	s_add_i32 s4, s4, s5
	s_add_u32 s24, s58, 0x2300000
	s_addc_u32 s25, s59, 0
	v_lshlrev_b32_e32 v72, 11, v72
	v_lshl_add_u32 v74, v30, 3, v72
	v_add_u32_e32 v74, s4, v74
	v_mov_b32_e32 v75, 0
	v_lshl_add_u64 v[74:75], s[24:25], 0, v[74:75]
	v_readlane_b32 s4, v254, 45
	s_nop 1
	s_add_i32 s15, s15, s4
	s_cmpk_gt_i32 s15, 0x3ff
	s_nop 7
	v_cvt_pk_bf16_f32 v46, v6, v7
	v_cvt_pk_bf16_f32 v47, v8, v9
	v_cvt_pk_bf16_f32 v48, v10, v11
	v_cvt_pk_bf16_f32 v49, v12, v13
	v_cvt_pk_bf16_f32 v50, v14, v15
	v_cvt_pk_bf16_f32 v51, v16, v17
	v_cvt_pk_bf16_f32 v52, v18, v19
	v_cvt_pk_bf16_f32 v53, v20, v21
	global_store_dwordx2 v[74:75], v[46:47], off
	global_store_dwordx2 v[74:75], v[48:49], off offset:16
	global_store_dwordx2 v[74:75], v[50:51], off offset:32
	global_store_dwordx2 v[74:75], v[52:53], off offset:48
	s_barrier
	v_readlane_b32 s5, v254, 46
	s_cbranch_scc0 .LBB0_779
